# mc_item<2> item head: 4 Q-row staging loads issued together with the 12 K/V loads; LDS stores delayed behind counted vmcnt
# baseline (speedup 1.0000x reference)
; #define LAS __attribute__((address_space(3)))
; template <int TY> __device__ __forceinline__ void mc_item(const Params& p, ldsp lds, int item) {
;     ...
;     ldsp QX = lds, QH2 = lds + o_qh, KTs = lds + o_kt, VTs = lds + o_vt, Pm = lds + o_pm; LAS float* RED = (LAS float*)(lds + o_red);
;     const bf16_t* Pb = (const bf16_t*)(p.ws + WS_P);
;     constexpr int PP = TY == 2 ? NO : NE;
;     const int ecol = TY ? 256 + h * 128 : h * 64;
;     if (TY == 2) stage_rows<DK>(QX, PQ, Pb + (size_t)row0 * NO + O_Q + h * 256, NO, tid);
;     else { stage_rows<DK>(QX, PQ, (const bf16_t*)(p.ws + WS_QT) + (size_t)row0 * 768 + ecol, 768, tid);
;            stage_rows<DK>(QH2, PQ, (const bf16_t*)(p.ws + WS_QH) + (size_t)row0 * 768 + ecol, 768, tid); }
;     f32x4 acc[ET][4];
; #pragma unroll
;     for (int ei = 0; ei < ET; ++ei)
; #pragma unroll
;         for (int tk = 0; tk < 4; ++tk) acc[ei][tk] = (f32x4){0.f, 0.f, 0.f, 0.f};
;     const int voff = TY == 0 ? E_VA + h * 128 : (TY == 1 ? E_IB + h * 128 : O_V + h * 512);
;     const int tt = wave & 3, sp = wave >> 2;
;     u32x4 kr[TY == 2 ? 4 : 1], vr[TY == 2 ? 8 : 1];
;     if constexpr (TY == 2) { const size_t rowq = (size_t)b * 2048 + (sc * NB) * 64;
;         ld_rows<256>(kr, Pb + rowq * NO + O_K + h * 256, NO, tid); ld_T<512>(vr, Pb + rowq * NO + voff, NO, wave, lane); }
.LBB0_878:
	s_lshr_b32 s0, s37, 8
	s_add_i32 s1, s37, s0
	s_and_b32 s40, s1, 31
	s_ashr_i32 s20, s37, 7
	v_mov_b32_e32 v152, v161
	s_lshl_b32 s10, s20, 11
	s_lshl_b32 s11, s40, 6
	s_ashr_i32 s8, s37, 5
	s_or_b32 s58, s11, s10
	v_ashrrev_i32_e32 v0, 31, v152
	s_and_b32 s9, s8, 3
	s_mul_i32 s11, s58, 0x3000
	v_lshrrev_b32_e32 v0, 27, v0
	s_mul_hi_i32 s10, s58, 0x3000
	s_add_u32 s11, s26, s11
	v_add_u32_e32 v0, v152, v0
	s_addc_u32 s12, s27, s10
	s_lshl_b32 s59, s9, 9
	v_ashrrev_i32_e32 v62, 5, v0
	v_and_b32_e32 v0, 0xffffffe0, v0
	s_add_u32 s10, s11, s59
	v_sub_u32_e32 v60, v152, v0
	s_addc_u32 s11, s12, 0
	v_lshlrev_b32_e32 v42, 3, v60
	v_mov_b64_e32 v[4:5], s[10:11]
	v_ashrrev_i32_e32 v43, 31, v42
	v_mad_i64_i32 v[0:1], s[10:11], v62, s56, v[4:5]
	v_lshlrev_b64 v[6:7], 1, v[42:43]
	v_lshl_add_u64 v[0:1], v[0:1], 0, v[6:7]
	global_load_dwordx4 v[134:137], v[0:1], off
	s_movk_i32 s16, 0x108
	v_mad_u64_u32 v[8:9], s[10:11], v62, s16, v[42:43]
	v_lshl_add_u32 v8, v8, 1, 0
	s_ashr_i32 s21, s20, 31
	s_and_b32 s14, s1, 28
	s_lshl_b32 s14, s14, 6
	v_readfirstlane_b32 s60, v152
	s_ashr_i32 s12, s60, 6
	s_and_b32 s13, s1, 3
	s_lshl_b32 s9, s9, 10
	v_bfe_u32 v70, v152, 5, 1
	v_lshl_add_u32 v206, v60, 4, 0
	v_and_b32_e32 v150, 15, v152
	v_bfe_u32 v68, v152, 4, 2
	v_lshlrev_b32_e32 v138, 3, v68
	v_lshlrev_b32_e32 v151, 2, v68
	v_and_b32_e32 v153, 48, v152
	v_mul_u32_u24_e32 v225, 0x90, v150
	s_nop 0
	v_mov_b32_e32 v148, v8
	v_add_u32_e32 v0, 0x200, v152
	v_ashrrev_i32_e32 v1, 31, v0
	v_lshrrev_b32_e32 v1, 27, v1
	v_add_u32_e32 v1, v0, v1
	v_ashrrev_i32_e32 v63, 5, v1
	v_and_b32_e32 v1, 0xffffffe0, v1
	v_sub_u32_e32 v61, v0, v1
	v_lshlrev_b32_e32 v44, 3, v61
	v_ashrrev_i32_e32 v45, 31, v44
	v_mad_i64_i32 v[0:1], s[10:11], v63, s56, v[4:5]
	v_lshlrev_b64 v[8:9], 1, v[44:45]
	v_lshl_add_u64 v[0:1], v[0:1], 0, v[8:9]
	global_load_dwordx4 v[140:143], v[0:1], off
	v_mad_u64_u32 v[10:11], s[10:11], v63, s16, v[44:45]
	v_lshl_add_u32 v10, v10, 1, 0
	v_lshl_add_u32 v207, v61, 4, 0
	s_nop 0
	v_mov_b32_e32 v149, v10
	v_add_u32_e32 v0, 0x400, v152
	v_ashrrev_i32_e32 v1, 31, v0
	v_lshrrev_b32_e32 v1, 27, v1
	v_add_u32_e32 v1, v0, v1
	v_ashrrev_i32_e32 v64, 5, v1
	v_and_b32_e32 v1, 0xffffffe0, v1
	v_sub_u32_e32 v66, v0, v1
	v_lshlrev_b32_e32 v50, 3, v66
	v_ashrrev_i32_e32 v51, 31, v50
	v_mad_i64_i32 v[0:1], s[10:11], v64, s56, v[4:5]
	v_lshlrev_b64 v[10:11], 1, v[50:51]
	v_lshl_add_u64 v[0:1], v[0:1], 0, v[10:11]
	global_load_dwordx4 v[144:147], v[0:1], off
	v_mad_u64_u32 v[12:13], s[10:11], v64, s16, v[50:51]
	v_lshl_add_u32 v12, v12, 1, 0
	v_lshl_add_u32 v208, v66, 4, 0
	s_nop 0
	v_mov_b32_e32 v162, v12
	v_add_u32_e32 v0, 0x600, v152
	v_ashrrev_i32_e32 v1, 31, v0
	v_lshrrev_b32_e32 v1, 27, v1
	v_add_u32_e32 v1, v0, v1
	v_ashrrev_i32_e32 v65, 5, v1
	v_and_b32_e32 v1, 0xffffffe0, v1
	v_sub_u32_e32 v67, v0, v1
	v_lshlrev_b32_e32 v52, 3, v67
	v_ashrrev_i32_e32 v53, 31, v52
	v_mad_i64_i32 v[0:1], s[10:11], v65, s56, v[4:5]
	v_lshlrev_b64 v[4:5], 1, v[52:53]
	v_lshl_add_u64 v[0:1], v[0:1], 0, v[4:5]
	global_load_dwordx4 v[154:157], v[0:1], off
	v_mad_u64_u32 v[12:13], s[10:11], v65, s16, v[52:53]
	s_lshl_b64 s[10:11], s[20:21], 11
	s_or_b32 s10, s10, s14
	s_mulk_i32 s11, 0x3000
	s_mul_hi_u32 s14, s10, 0x3000
	s_add_i32 s14, s14, s11
	s_mulk_i32 s10, 0x3000
	s_add_u32 s15, s26, s10
	s_addc_u32 s14, s27, s14
	s_add_u32 s10, s15, s59
	v_lshl_add_u32 v12, v12, 1, 0
	s_addc_u32 s11, s14, 0
	s_bitset1_b32 s9, 12
	v_lshl_add_u32 v210, v67, 4, 0
	s_nop 0
	v_mov_b32_e32 v163, v12
	v_mov_b64_e32 v[0:1], s[10:11]
	v_mad_i64_i32 v[2:3], s[10:11], v62, s56, v[0:1]
	v_lshl_add_u64 v[2:3], v[2:3], 0, v[6:7]
	global_load_dwordx4 v[30:33], v[2:3], off offset:2048
	v_mad_i64_i32 v[2:3], s[10:11], v63, s56, v[0:1]
	v_lshl_add_u64 v[2:3], v[2:3], 0, v[8:9]
	global_load_dwordx4 v[34:37], v[2:3], off offset:2048
	v_mad_i64_i32 v[2:3], s[10:11], v64, s56, v[0:1]
	v_mad_i64_i32 v[0:1], s[10:11], v65, s56, v[0:1]
	v_lshl_add_u64 v[2:3], v[2:3], 0, v[10:11]
	v_lshl_add_u64 v[0:1], v[0:1], 0, v[4:5]
	s_add_u32 s10, s15, s9
	global_load_dwordx4 v[38:41], v[2:3], off offset:2048
	global_load_dwordx4 v[46:49], v[0:1], off offset:2048
	s_addc_u32 s11, s14, 0
	s_lshl_b32 s9, s12, 5
	v_and_b32_e32 v0, 31, v152
	v_and_or_b32 v69, s9, 32, v0
	s_and_b32 s9, s12, 0x1ffffffe
	v_mul_u32_u24_e32 v0, 0x1800, v69
	v_or_b32_e32 v2, s9, v70
	v_lshlrev_b32_e32 v16, 1, v0
	v_lshlrev_b32_e32 v58, 3, v2
	v_lshl_add_u64 v[0:1], s[10:11], 0, v[16:17]
	v_ashrrev_i32_e32 v59, 31, v58
	v_lshl_add_u64 v[54:55], v[58:59], 1, v[0:1]
	global_load_dwordx4 v[26:29], v[54:55], off
	global_load_dwordx4 v[22:25], v[54:55], off offset:128
	global_load_dwordx4 v[18:21], v[54:55], off offset:256
	global_load_dwordx4 v[12:15], v[54:55], off offset:384
	global_load_dwordx4 v[8:11], v[54:55], off offset:512
	global_load_dwordx4 v[4:7], v[54:55], off offset:640
	global_load_dwordx4 v[0:3], v[54:55], off offset:768
	s_nop 0
	global_load_dwordx4 v[54:57], v[54:55], off offset:896
	s_waitcnt vmcnt(15)
	ds_write_b128 v148, v[134:137]
	s_waitcnt vmcnt(14)
	ds_write_b128 v149, v[140:143]
	s_waitcnt vmcnt(13)
	ds_write_b128 v162, v[144:147]
	s_waitcnt vmcnt(12)
	ds_write_b128 v163, v[154:157]
	s_movk_i32 s9, 0x210
	v_mul_lo_u32 v203, v62, s9
	v_mul_lo_u32 v204, v63, s9
	v_mul_lo_u32 v205, v64, s9
	v_mul_lo_u32 v209, v65, s9
	s_and_b32 s9, s12, 0x3fffffe
	v_or_b32_e32 v60, s9, v70
	s_movk_i32 s9, 0x240
	v_mul_lo_u32 v60, v60, s9
	s_lshl_b32 s9, s12, 4
	v_and_or_b32 v155, s9, 48, v150
	s_ashr_i32 s9, s60, 3
	v_or_b32_e32 v60, v69, v60
	v_readlane_b32 s14, v255, 22
	s_andn2_b32 s9, s9, 31
	v_or_b32_e32 v157, s9, v151
	v_lshl_add_u32 v162, v60, 1, s14
	v_or_b32_e32 v60, s9, v150
	v_mad_u64_u32 v[60:61], s[10:11], v60, s16, v[138:139]
	v_readlane_b32 s9, v255, 23
	v_mul_u32_u24_e32 v61, 0x48, v155
	v_mul_u32_u24_e32 v67, 0x108, v155
	v_add_u32_e32 v154, s9, v153
	s_and_b32 s9, s60, 0x7fffffc0
	v_add_u32_e32 v66, 0x1080, v60
	v_add_lshl_u32 v156, v157, v61, 1
	v_or_b32_e32 v61, s9, v150
	s_movk_i32 s9, 0x90
	v_add_u32_e32 v139, s14, v153
	s_cmp_lg_u32 s13, 0
	v_add_lshl_u32 v163, v67, v138, 1
	v_lshlrev_b32_e32 v218, 1, v60
	v_lshlrev_b32_e32 v219, 1, v66
	v_or_b32_e32 v220, 16, v157
	v_or_b32_e32 v221, 17, v157
	v_or_b32_e32 v222, 18, v157
	v_or_b32_e32 v223, 3, v157
	v_or_b32_e32 v224, 19, v157
	v_mul_lo_u32 v226, v61, s9
	s_cbranch_scc0 .LBB0_897
; template <int TY> __device__ __forceinline__ void mc_item(const Params& p, ldsp lds, int item) {
;     ...
;     f32x4 acc[ET][4];
; #pragma unroll
;     for (int ei = 0; ei < ET; ++ei)
; #pragma unroll
;         for (int tk = 0; tk < 4; ++tk) acc[ei][tk] = (f32x4){0.f, 0.f, 0.f, 0.f};
;     const int voff = TY == 0 ? E_VA + h * 128 : (TY == 1 ? E_IB + h * 128 : O_V + h * 512);
;     const int tt = wave & 3, sp = wave >> 2;
;     u32x4 kr[TY == 2 ? 4 : 1], vr[TY == 2 ? 8 : 1];
;     if constexpr (TY == 2) { const size_t rowq = (size_t)b * 2048 + (sc * NB) * 64;
;         ld_rows<256>(kr, Pb + rowq * NO + O_K + h * 256, NO, tid); ld_T<512>(vr, Pb + rowq * NO + voff, NO, wave, lane); }
;     for (int j = 0; j <= jc; ++j) { const size_t rowj = (size_t)b * 2048 + (sc * NB + j) * 64;
;         if constexpr (TY == 2) { st_rows<256>(KTs, PQ, kr, tid); st_T<512>(VTs, 72, vr, wave, lane); }
;         else { stage_rows<DK>(KTs, PQ, (const bf16_t*)(p.ws + WS_KT) + rowj * 768 + ecol, 768, tid);
;                stage_T<DV>(VTs, 72, Pb + rowj * PP + voff, PP, wave, lane); }
;         if constexpr (TY == 2) { __syncthreads(); if (j < jc) { const size_t rown = rowj + 64; ld_rows<256>(kr, Pb + rown * NO + O_K + h * 256, NO, tid); ld_T<512>(vr, Pb + rown * NO + voff, NO, wave, lane); } }
	s_movk_i32 s38, 0x90
	s_bfe_u32 s1, s1, 0x30002
	s_add_i32 s0, s36, s0
	s_mul_i32 s21, s1, 0x300000
	s_and_b32 s0, s0, 3
	v_mul_lo_u32 v202, v61, s38
	s_mul_hi_i32 s38, s20, 0x1800000
	s_mul_i32 s20, s20, 0x1800000
	s_add_u32 s39, s20, s21
	s_addc_u32 s21, s38, 0
	s_lshl_b32 s20, s37, 4
	s_and_b32 s20, s20, 0x600
	v_mad_i64_i32 v[68:69], s[10:11], v62, s56, 0
	s_or_b32 s20, s39, s20
	v_lshlrev_b32_e32 v217, 1, v60
	v_lshl_add_u64 v[60:61], s[20:21], 0, v[68:69]
	v_readlane_b32 s76, v254, 55
	v_mad_i64_i32 v[62:63], s[10:11], v63, s56, 0
	v_lshl_add_u64 v[42:43], v[42:43], 1, v[60:61]
	v_readlane_b32 s77, v254, 56
	v_mad_i64_i32 v[70:71], s[10:11], v64, s56, 0
	s_nop 0
	v_lshl_add_u64 v[140:141], s[76:77], 0, v[42:43]
	v_lshl_add_u64 v[42:43], s[20:21], 0, v[62:63]
	v_lshl_add_u64 v[42:43], v[44:45], 1, v[42:43]
	v_lshl_add_u64 v[142:143], s[76:77], 0, v[42:43]
	v_lshl_add_u64 v[42:43], s[20:21], 0, v[70:71]
	v_mad_i64_i32 v[64:65], s[10:11], v65, s56, 0
	v_lshl_add_u64 v[42:43], v[50:51], 1, v[42:43]
	v_lshl_add_u64 v[144:145], s[76:77], 0, v[42:43]
	v_lshl_add_u64 v[42:43], s[20:21], 0, v[64:65]
	s_lshl_b32 s20, s37, 5
	s_and_b32 s20, s20, 0xc00
	v_lshl_add_u64 v[42:43], v[52:53], 1, v[42:43]
	s_or_b32 s20, s39, s20
	v_lshl_add_u64 v[146:147], s[76:77], 0, v[42:43]
	v_mov_b32_e32 v42, s20
	v_mov_b32_e32 v43, s21
	v_lshl_add_u64 v[42:43], v[58:59], 1, v[42:43]
	v_readlane_b32 s20, v254, 57
	s_movk_i32 s10, 0xfff
	v_lshl_add_u64 v[42:43], v[42:43], 0, v[16:17]
	v_readlane_b32 s21, v254, 58
	s_mul_i32 s9, s0, 0xc0000
	v_cmp_lt_i32_e64 s[0:1], s57, v157
	v_or_b32_e32 v215, 16, v157
	v_cmp_lt_i32_e64 s[10:11], s10, v157
	v_or_b32_e32 v214, 17, v157
	v_or_b32_e32 v211, 18, v157
	v_or_b32_e32 v212, 3, v157
	v_or_b32_e32 v213, 19, v157
	v_lshl_add_u64 v[148:149], s[20:21], 0, v[42:43]
	v_mov_b32_e32 v42, 0
	s_waitcnt vmcnt(0)
	v_mov_b64_e32 v[100:101], v[56:57]
	v_mov_b64_e32 v[132:133], v[32:33]
	v_mov_b64_e32 v[128:129], v[36:37]
	v_mov_b64_e32 v[124:125], v[40:41]
	v_mov_b64_e32 v[120:121], v[48:49]
	v_lshlrev_b32_e32 v216, 1, v66
	v_cmp_lt_i32_e32 vcc, s57, v215
	v_cmp_lt_i32_e64 s[12:13], s57, v214
	v_cmp_lt_i32_e64 s[14:15], s57, v211
	v_cmp_lt_i32_e64 s[16:17], s57, v212
	v_cmp_lt_i32_e64 s[18:19], s57, v213
	v_mul_u32_u24_e32 v201, 0x90, v150
	v_add_u32_e32 v160, 0x900, v202
	v_add_u32_e32 v159, 0x1200, v202
	v_add_u32_e32 v158, 0x1b00, v202
	s_mov_b64 s[38:39], 0
	s_and_b64 s[20:21], s[10:11], s[0:1]
	v_mov_b64_e32 v[98:99], v[54:55]
	v_mov_b64_e32 v[130:131], v[30:31]
	v_mov_b64_e32 v[126:127], v[34:35]
	v_mov_b64_e32 v[122:123], v[38:39]
	v_mov_b64_e32 v[118:119], v[46:47]
	v_mov_b32_e32 v43, v42
	v_mov_b32_e32 v44, v42
	v_mov_b32_e32 v45, v42
	v_mov_b32_e32 v50, v42
	v_mov_b32_e32 v51, v42
	v_mov_b32_e32 v52, v42
	v_mov_b32_e32 v53, v42
	v_mov_b32_e32 v58, v42
	v_mov_b32_e32 v59, v42
	v_mov_b32_e32 v60, v42
	v_mov_b32_e32 v61, v42
	v_mov_b32_e32 v62, v42
	v_mov_b32_e32 v63, v42
	v_mov_b32_e32 v64, v42
	v_mov_b32_e32 v65, v42
	v_mov_b32_e32 v66, v42
	v_mov_b32_e32 v67, v42
	v_mov_b32_e32 v68, v42
	v_mov_b32_e32 v69, v42
	v_mov_b32_e32 v70, v42
	v_mov_b32_e32 v71, v42
	v_mov_b32_e32 v72, v42
	v_mov_b32_e32 v73, v42
	v_mov_b32_e32 v74, v42
	v_mov_b32_e32 v75, v42
	v_mov_b32_e32 v76, v42
	v_mov_b32_e32 v77, v42
	v_mov_b32_e32 v78, v42
	v_mov_b32_e32 v79, v42
	v_mov_b32_e32 v80, v42
	v_mov_b32_e32 v81, v42
	v_mov_b32_e32 v82, v42
	v_mov_b32_e32 v83, v42
	v_mov_b32_e32 v84, v42
	v_mov_b32_e32 v85, v42
	v_mov_b32_e32 v86, v42
	v_mov_b32_e32 v87, v42
	v_mov_b32_e32 v88, v42
	v_mov_b32_e32 v89, v42
	v_mov_b32_e32 v90, v42
	v_mov_b32_e32 v91, v42
	v_mov_b32_e32 v92, v42
	v_mov_b32_e32 v93, v42
	v_mov_b32_e32 v94, v42
	v_mov_b32_e32 v95, v42
	v_mov_b32_e32 v96, v42
	v_mov_b32_e32 v97, v42
	v_mov_b32_e32 v102, v42
	v_mov_b32_e32 v103, v42
	v_mov_b32_e32 v104, v42
	v_mov_b32_e32 v105, v42
	v_mov_b32_e32 v106, v42
	v_mov_b32_e32 v107, v42
	v_mov_b32_e32 v108, v42
	v_mov_b32_e32 v109, v42
	v_mov_b32_e32 v110, v42
	v_mov_b32_e32 v111, v42
	v_mov_b32_e32 v112, v42
	v_mov_b32_e32 v113, v42
	v_mov_b32_e32 v114, v42
	v_mov_b32_e32 v115, v42
	v_mov_b32_e32 v116, v42
	v_mov_b32_e32 v117, v42
